# on top of v193: nt hints on the input-row (x) loads of ROW0 and ROW1
# baseline (speedup 1.0000x reference)
.LBB0_326:
	s_or_b64 exec, exec, s[14:15]
	v_lshl_add_u64 v[2:3], v[0:1], 0, v[14:15]
	global_load_dwordx4 v[40:43], v[2:3], off nt
	global_load_dwordx4 v[44:47], v[2:3], off offset:1024 nt
	global_load_dwordx4 v[48:51], v[2:3], off offset:2048 nt
	global_load_dwordx4 v[52:55], v[2:3], off offset:3072 nt
	v_lshl_add_u64 v[2:3], v[0:1], 0, v[16:17]
	v_lshl_add_u64 v[60:61], v[0:1], 0, v[18:19]
	global_load_dwordx4 v[56:59], v[2:3], off nt
	s_nop 0
	global_load_dwordx4 v[60:63], v[60:61], off nt
	v_lshl_add_u64 v[2:3], v[0:1], 0, v[20:21]
	v_lshl_add_u64 v[0:1], v[0:1], 0, v[22:23]
	global_load_dwordx4 v[64:67], v[2:3], off nt
	s_nop 0
	global_load_dwordx4 v[0:3], v[0:1], off nt
	v_lshrrev_b32_e32 v6, 3, v6
	v_ashrrev_i32_e32 v39, 12, v4
	v_add_u32_e32 v6, 2, v6
	v_cndmask_b32_e32 v6, v6, v39, vcc
	v_mad_i64_i32 v[124:125], s[4:5], v6, s28, v[12:13]
	v_lshl_add_u64 v[126:127], v[124:125], 0, s[12:13]
	v_lshl_add_u64 v[68:69], v[126:127], 0, v[14:15]
	v_lshl_add_u64 v[96:97], v[124:125], 0, v[14:15]
	v_lshl_add_u64 v[92:93], v[126:127], 0, v[24:25]
	v_lshl_add_u64 v[84:85], v[126:127], 0, v[26:27]
	v_lshl_add_u64 v[88:89], v[126:127], 0, v[28:29]
	global_load_dwordx4 v[68:71], v[68:69], off
	s_nop 0
	global_load_dwordx4 v[72:75], v[96:97], off
	global_load_dwordx4 v[76:79], v[96:97], off offset:1024
	global_load_dwordx4 v[80:83], v[96:97], off offset:2048
	s_nop 0
	global_load_dwordx4 v[84:87], v[84:85], off
	s_nop 0
	global_load_dwordx4 v[88:91], v[88:89], off
	s_nop 0
	global_load_dwordx4 v[92:95], v[92:93], off
	s_nop 0
	global_load_dwordx4 v[96:99], v[96:97], off offset:3072
	v_lshl_add_u64 v[100:101], v[126:127], 0, v[16:17]
	v_lshl_add_u64 v[104:105], v[124:125], 0, v[16:17]
	v_lshl_add_u64 v[108:109], v[126:127], 0, v[18:19]
	v_lshl_add_u64 v[112:113], v[124:125], 0, v[18:19]
	v_lshl_add_u64 v[116:117], v[126:127], 0, v[20:21]
	v_lshl_add_u64 v[120:121], v[124:125], 0, v[20:21]
	v_lshl_add_u64 v[126:127], v[126:127], 0, v[22:23]
	v_lshl_add_u64 v[130:131], v[124:125], 0, v[22:23]
	global_load_dwordx4 v[100:103], v[100:101], off
	s_nop 0
	global_load_dwordx4 v[104:107], v[104:105], off
	s_nop 0
	global_load_dwordx4 v[108:111], v[108:109], off
	s_nop 0
	global_load_dwordx4 v[112:115], v[112:113], off
	s_nop 0
	global_load_dwordx4 v[116:119], v[116:117], off
	s_nop 0
	global_load_dwordx4 v[120:123], v[120:121], off
	s_nop 0
	global_load_dwordx4 v[124:127], v[126:127], off
	s_nop 0
	global_load_dwordx4 v[130:133], v[130:131], off
	s_waitcnt vmcnt(23)
	v_mov_b32_e32 v136, v41
	s_waitcnt vmcnt(22)
	v_mov_b32_e32 v137, v45
	v_mov_b32_e32 v134, v40
	v_mov_b32_e32 v135, v44
	v_pk_mul_f32 v[136:137], v[136:137], v[136:137]
	v_mov_b32_e32 v138, v43
	v_mov_b32_e32 v139, v47
	v_pk_fma_f32 v[134:135], v[134:135], v[134:135], v[136:137]
	v_mov_b32_e32 v136, v42
	v_mov_b32_e32 v137, v46
	v_pk_mul_f32 v[138:139], v[138:139], v[138:139]
	s_waitcnt vmcnt(19)
	v_mul_f32_e32 v6, v56, v56
	v_pk_fma_f32 v[136:137], v[136:137], v[136:137], v[138:139]
	v_pk_mul_f32 v[138:139], v[48:49], v[48:49]
	v_pk_add_f32 v[134:135], v[134:135], v[136:137]
	v_pk_mul_f32 v[136:137], v[50:51], v[50:51]
	v_mul_f32_e32 v39, v57, v57
	v_pk_mov_b32 v[140:141], v[138:139], v[136:137] op_sel:[1,0]
	v_mov_b32_e32 v139, v137
	v_pk_add_f32 v[136:137], v[140:141], v[138:139]
	v_pk_add_f32 v[134:135], v[134:135], v[134:135] op_sel:[0,1] op_sel_hi:[1,0]
	v_pk_add_f32 v[136:137], v[136:137], v[136:137] op_sel:[0,1] op_sel_hi:[1,0]
	v_mov_b32_e32 v135, v6
	v_mov_b32_e32 v137, v39
	v_mul_f32_e32 v6, v53, v53
	v_pk_add_f32 v[134:135], v[134:135], v[136:137]
	v_pk_fma_f32 v[136:137], v[52:53], v[52:53], v[6:7] op_sel_hi:[1,1,0]
	v_mul_f32_e32 v6, v55, v55
	v_mul_f32_e32 v129, v58, v58
	v_mul_f32_e32 v140, v59, v59
	v_pk_fma_f32 v[138:139], v[54:55], v[54:55], v[6:7] op_sel_hi:[1,1,0]
	v_mov_b32_e32 v137, v129
	v_mov_b32_e32 v139, v140
	v_pk_add_f32 v[136:137], v[136:137], v[138:139]
	s_waitcnt vmcnt(18)
	v_pk_mul_f32 v[138:139], v[60:61], v[60:61]
	v_pk_add_f32 v[134:135], v[134:135], v[136:137]
	v_pk_mul_f32 v[136:137], v[62:63], v[62:63]
	s_waitcnt vmcnt(16)
	v_mul_f32_e32 v6, v0, v0
	v_pk_mov_b32 v[140:141], v[138:139], v[136:137] op_sel:[1,0]
	v_mov_b32_e32 v139, v137
	v_pk_add_f32 v[136:137], v[140:141], v[138:139]
	v_mul_f32_e32 v39, v1, v1
	v_pk_add_f32 v[134:135], v[134:135], v[134:135] op_sel:[0,1] op_sel_hi:[1,0]
	v_pk_add_f32 v[136:137], v[136:137], v[136:137] op_sel:[0,1] op_sel_hi:[1,0]
	v_mov_b32_e32 v135, v6
	v_mov_b32_e32 v137, v39
	v_mul_f32_e32 v6, v65, v65
	v_pk_add_f32 v[134:135], v[134:135], v[136:137]
	v_pk_fma_f32 v[136:137], v[64:65], v[64:65], v[6:7] op_sel_hi:[1,1,0]
	v_mul_f32_e32 v6, v67, v67
	v_mul_f32_e32 v129, v2, v2
	v_mul_f32_e32 v140, v3, v3
	v_pk_fma_f32 v[138:139], v[66:67], v[66:67], v[6:7] op_sel_hi:[1,1,0]
	v_mov_b32_e32 v137, v129
	v_mov_b32_e32 v139, v140
	v_pk_add_f32 v[136:137], v[136:137], v[138:139]
	v_lshlrev_b64 v[30:31], 12, v[30:31]
	v_pk_add_f32 v[134:135], v[134:135], v[136:137]
	v_lshl_add_u64 v[30:31], v[8:9], 0, v[30:31]
	v_add_f32_e32 v6, v134, v135
	ds_bpermute_b32 v39, v32, v6
	v_lshl_add_u64 v[4:5], v[4:5], 0, s[2:3]
	v_lshl_add_u64 v[10:11], v[10:11], 0, s[8:9]
	s_waitcnt lgkmcnt(0)
	v_add_f32_e32 v6, v6, v39
	ds_bpermute_b32 v39, v33, v6
	s_waitcnt lgkmcnt(0)
	v_add_f32_e32 v6, v6, v39
	ds_bpermute_b32 v39, v34, v6
	s_waitcnt lgkmcnt(0)
	v_add_f32_e32 v6, v6, v39
	ds_bpermute_b32 v39, v35, v6
	s_waitcnt lgkmcnt(0)
	v_add_f32_e32 v6, v6, v39
	ds_bpermute_b32 v39, v36, v6
	s_waitcnt lgkmcnt(0)
	v_add_f32_e32 v6, v6, v39
	ds_bpermute_b32 v39, v37, v6
	s_waitcnt lgkmcnt(0)
	v_add_f32_e32 v6, v6, v39
	v_fmamk_f32 v6, v6, 0x3a000000, v38
	v_mul_f32_e32 v39, 0x4b800000, v6
	v_cmp_gt_f32_e32 vcc, s29, v6
	s_nop 1
	v_cndmask_b32_e32 v6, v6, v39, vcc
	v_rsq_f32_e32 v6, v6
	s_nop 0
	v_mul_f32_e32 v39, 0x45800000, v6
	v_cndmask_b32_e32 v6, v6, v39, vcc
	v_pk_mul_f32 v[40:41], v[40:41], v[6:7] op_sel_hi:[1,0]
	v_pk_mul_f32 v[42:43], v[42:43], v[6:7] op_sel_hi:[1,0]
	s_waitcnt vmcnt(14)
	v_pk_fma_f32 v[40:41], v[68:69], v[40:41], v[72:73]
	v_pk_fma_f32 v[42:43], v[70:71], v[42:43], v[74:75]
	v_cvt_pk_bf16_f32 v40, v40, v41
	v_cvt_pk_bf16_f32 v41, v42, v43
	global_store_dwordx2 v[30:31], v[40:41], off
	v_pk_mul_f32 v[40:41], v[44:45], v[6:7] op_sel_hi:[1,0]
	v_pk_mul_f32 v[42:43], v[46:47], v[6:7] op_sel_hi:[1,0]
	s_waitcnt vmcnt(10)
	v_pk_fma_f32 v[40:41], v[92:93], v[40:41], v[76:77]
	v_pk_fma_f32 v[42:43], v[94:95], v[42:43], v[78:79]
	v_cvt_pk_bf16_f32 v40, v40, v41
	v_cvt_pk_bf16_f32 v41, v42, v43
	global_store_dwordx2 v[30:31], v[40:41], off offset:512
	v_pk_mul_f32 v[40:41], v[48:49], v[6:7] op_sel_hi:[1,0]
	v_pk_mul_f32 v[42:43], v[50:51], v[6:7] op_sel_hi:[1,0]
	v_pk_fma_f32 v[40:41], v[84:85], v[40:41], v[80:81]
	v_pk_fma_f32 v[42:43], v[86:87], v[42:43], v[82:83]
	v_cvt_pk_bf16_f32 v40, v40, v41
	v_cvt_pk_bf16_f32 v41, v42, v43
	global_store_dwordx2 v[30:31], v[40:41], off offset:1024
	v_pk_mul_f32 v[40:41], v[52:53], v[6:7] op_sel_hi:[1,0]
	v_pk_mul_f32 v[42:43], v[54:55], v[6:7] op_sel_hi:[1,0]
	s_waitcnt vmcnt(11)
	v_pk_fma_f32 v[40:41], v[88:89], v[40:41], v[96:97]
	v_pk_fma_f32 v[42:43], v[90:91], v[42:43], v[98:99]
	v_cvt_pk_bf16_f32 v40, v40, v41
	v_cvt_pk_bf16_f32 v41, v42, v43
	global_store_dwordx2 v[30:31], v[40:41], off offset:1536
	v_pk_mul_f32 v[40:41], v[56:57], v[6:7] op_sel_hi:[1,0]
	v_pk_mul_f32 v[42:43], v[58:59], v[6:7] op_sel_hi:[1,0]
	s_waitcnt vmcnt(10)
	v_pk_fma_f32 v[40:41], v[100:101], v[40:41], v[104:105]
	v_pk_fma_f32 v[42:43], v[102:103], v[42:43], v[106:107]
	v_cvt_pk_bf16_f32 v40, v40, v41
	v_cvt_pk_bf16_f32 v41, v42, v43
	global_store_dwordx2 v[30:31], v[40:41], off offset:2048
	v_pk_mul_f32 v[40:41], v[60:61], v[6:7] op_sel_hi:[1,0]
	v_pk_mul_f32 v[42:43], v[62:63], v[6:7] op_sel_hi:[1,0]
	s_waitcnt vmcnt(9)
	v_pk_fma_f32 v[40:41], v[108:109], v[40:41], v[112:113]
	v_pk_fma_f32 v[42:43], v[110:111], v[42:43], v[114:115]
	v_cvt_pk_bf16_f32 v40, v40, v41
	v_cvt_pk_bf16_f32 v41, v42, v43
	global_store_dwordx2 v[30:31], v[40:41], off offset:2560
	v_pk_mul_f32 v[40:41], v[64:65], v[6:7] op_sel_hi:[1,0]
	v_pk_mul_f32 v[42:43], v[66:67], v[6:7] op_sel_hi:[1,0]
	v_pk_mul_f32 v[0:1], v[0:1], v[6:7] op_sel_hi:[1,0]
	v_pk_mul_f32 v[2:3], v[2:3], v[6:7] op_sel_hi:[1,0]
	s_waitcnt vmcnt(8)
	v_pk_fma_f32 v[42:43], v[118:119], v[42:43], v[122:123]
	v_pk_fma_f32 v[40:41], v[116:117], v[40:41], v[120:121]
	s_waitcnt vmcnt(6)
	v_pk_fma_f32 v[2:3], v[126:127], v[2:3], v[132:133]
	v_pk_fma_f32 v[0:1], v[124:125], v[0:1], v[130:131]
	v_cmp_lt_i32_e32 vcc, s30, v4
	v_cvt_pk_bf16_f32 v40, v40, v41
	v_cvt_pk_bf16_f32 v41, v42, v43
	v_cvt_pk_bf16_f32 v0, v0, v1
	v_cvt_pk_bf16_f32 v1, v2, v3
	s_or_b64 s[10:11], vcc, s[10:11]
	global_store_dwordx2 v[30:31], v[40:41], off offset:3072
	global_store_dwordx2 v[30:31], v[0:1], off offset:3584
	s_andn2_b64 exec, exec, s[10:11]
	s_cbranch_execz .LBB0_329

.LBB0_737:
	s_or_b64 exec, exec, s[4:5]
	v_lshrrev_b32_e32 v32, 3, v134
	v_lshlrev_b32_e32 v134, 2, v132
	v_lshl_add_u64 v[2:3], v[0:1], 0, v[134:135]
	v_lshlrev_b32_e32 v162, 2, v142
	v_mov_b32_e32 v163, v135
	global_load_dwordx4 v[24:27], v[2:3], off nt
	global_load_dwordx4 v[20:23], v[2:3], off offset:1024 nt
	global_load_dwordx4 v[16:19], v[2:3], off offset:2048 nt
	global_load_dwordx4 v[12:15], v[2:3], off offset:3072 nt
	v_lshl_add_u64 v[2:3], v[0:1], 0, v[162:163]
	v_lshlrev_b32_e32 v160, 2, v144
	v_mov_b32_e32 v161, v135
	v_lshlrev_b32_e32 v158, 2, v146
	v_mov_b32_e32 v159, v135
	v_lshlrev_b32_e32 v156, 2, v148
	v_mov_b32_e32 v157, v135
	v_lshl_add_u64 v[4:5], v[0:1], 0, v[160:161]
	global_load_dwordx4 v[28:31], v[2:3], off nt
	global_load_dwordx4 v[8:11], v[4:5], off nt
	v_lshl_add_u64 v[2:3], v[0:1], 0, v[158:159]
	v_lshl_add_u64 v[0:1], v[0:1], 0, v[156:157]
	global_load_dwordx4 v[4:7], v[2:3], off nt
	s_nop 0
	global_load_dwordx4 v[0:3], v[0:1], off nt
	v_ashrrev_i32_e32 v33, 12, v130
	v_add_u32_e32 v32, 2, v32
	v_cndmask_b32_e32 v34, v32, v33, vcc
	v_mov_b64_e32 v[32:33], s[8:9]
	v_mad_i64_i32 v[64:65], s[4:5], v34, s58, v[32:33]
	v_lshlrev_b64 v[56:57], 11, v[154:155]
	v_or_b32_e32 v32, v56, v132
	v_mov_b32_e32 v33, v57
	v_lshlrev_b64 v[32:33], 1, v[32:33]
	v_lshl_add_u64 v[34:35], s[10:11], 0, v[32:33]
	v_lshl_add_u64 v[36:37], s[14:15], 0, v[32:33]
	v_lshl_add_u64 v[38:39], s[12:13], 0, v[32:33]
	v_lshl_add_u64 v[32:33], s[26:27], 0, v[32:33]
	global_load_dwordx2 v[100:101], v[34:35], off nt
	global_load_dwordx2 v[102:103], v[36:37], off nt
	global_load_dwordx2 v[104:105], v[38:39], off nt
	global_load_dwordx2 v[106:107], v[32:33], off nt
	v_or_b32_e32 v34, v56, v136
	v_mov_b32_e32 v35, v57
	v_lshl_add_u64 v[58:59], v[64:65], 0, s[52:53]
	v_lshlrev_b64 v[36:37], 1, v[34:35]
	v_lshl_add_u64 v[32:33], v[58:59], 0, v[134:135]
	v_lshl_add_u64 v[38:39], s[10:11], 0, v[36:37]
	global_load_dwordx4 v[32:35], v[32:33], off
	s_nop 0
	global_load_dwordx2 v[108:109], v[38:39], off nt
	v_lshl_add_u64 v[38:39], s[14:15], 0, v[36:37]
	v_lshl_add_u64 v[40:41], s[12:13], 0, v[36:37]
	v_lshl_add_u64 v[36:37], s[26:27], 0, v[36:37]
	global_load_dwordx2 v[110:111], v[38:39], off nt
	global_load_dwordx2 v[112:113], v[40:41], off nt
	global_load_dwordx2 v[114:115], v[36:37], off nt
	v_or_b32_e32 v38, v56, v138
	v_mov_b32_e32 v39, v57
	v_lshlrev_b32_e32 v66, 2, v136
	v_mov_b32_e32 v67, v135
	v_lshlrev_b64 v[40:41], 1, v[38:39]
	v_lshl_add_u64 v[36:37], v[58:59], 0, v[66:67]
	v_lshl_add_u64 v[42:43], s[10:11], 0, v[40:41]
	global_load_dwordx4 v[36:39], v[36:37], off
	s_nop 0
	global_load_dwordx2 v[116:117], v[42:43], off nt
	v_lshl_add_u64 v[42:43], s[14:15], 0, v[40:41]
	v_lshl_add_u64 v[44:45], s[12:13], 0, v[40:41]
	v_lshl_add_u64 v[40:41], s[26:27], 0, v[40:41]
	global_load_dwordx2 v[118:119], v[42:43], off nt
	global_load_dwordx2 v[120:121], v[44:45], off nt
	global_load_dwordx2 v[122:123], v[40:41], off nt
	v_or_b32_e32 v42, v56, v140
	v_mov_b32_e32 v43, v57
	v_lshlrev_b32_e32 v68, 2, v138
	v_mov_b32_e32 v69, v135
	v_lshlrev_b64 v[44:45], 1, v[42:43]
	v_lshl_add_u64 v[40:41], v[58:59], 0, v[68:69]
	v_lshl_add_u64 v[46:47], s[10:11], 0, v[44:45]
	global_load_dwordx4 v[40:43], v[40:41], off
	s_nop 0
	global_load_dwordx2 v[124:125], v[46:47], off nt
	v_lshl_add_u64 v[46:47], s[14:15], 0, v[44:45]
	v_lshl_add_u64 v[48:49], s[12:13], 0, v[44:45]
	v_lshl_add_u64 v[44:45], s[26:27], 0, v[44:45]
	global_load_dwordx2 v[126:127], v[46:47], off nt
	global_load_dwordx2 v[180:181], v[48:49], off nt
	global_load_dwordx2 v[182:183], v[44:45], off nt
	v_or_b32_e32 v46, v56, v142
	v_mov_b32_e32 v47, v57
	v_lshlrev_b32_e32 v70, 2, v140
	v_mov_b32_e32 v71, v135
	v_lshlrev_b64 v[48:49], 1, v[46:47]
	v_lshl_add_u64 v[44:45], v[58:59], 0, v[70:71]
	v_lshl_add_u64 v[50:51], s[10:11], 0, v[48:49]
	global_load_dwordx4 v[44:47], v[44:45], off
	s_nop 0
	global_load_dwordx2 v[184:185], v[50:51], off nt
	v_lshl_add_u64 v[50:51], s[14:15], 0, v[48:49]
	v_lshl_add_u64 v[52:53], s[12:13], 0, v[48:49]
	v_lshl_add_u64 v[48:49], s[26:27], 0, v[48:49]
	global_load_dwordx2 v[186:187], v[50:51], off nt
	global_load_dwordx2 v[98:99], v[52:53], off nt
	global_load_dwordx2 v[96:97], v[48:49], off nt
	v_or_b32_e32 v50, v56, v144
	v_mov_b32_e32 v51, v57
	v_lshlrev_b64 v[52:53], 1, v[50:51]
	v_lshl_add_u64 v[48:49], v[58:59], 0, v[162:163]
	v_lshl_add_u64 v[54:55], s[10:11], 0, v[52:53]
	global_load_dwordx4 v[48:51], v[48:49], off
	s_nop 0
	global_load_dwordx2 v[92:93], v[54:55], off nt
	v_lshl_add_u64 v[54:55], s[14:15], 0, v[52:53]
	v_lshl_add_u64 v[60:61], s[12:13], 0, v[52:53]
	v_lshl_add_u64 v[52:53], s[26:27], 0, v[52:53]
	global_load_dwordx2 v[94:95], v[54:55], off nt
	global_load_dwordx2 v[90:91], v[60:61], off nt
	global_load_dwordx2 v[88:89], v[52:53], off nt
	v_or_b32_e32 v54, v56, v146
	v_mov_b32_e32 v55, v57
	v_lshlrev_b64 v[60:61], 1, v[54:55]
	v_lshl_add_u64 v[52:53], v[58:59], 0, v[160:161]
	v_lshl_add_u64 v[62:63], s[10:11], 0, v[60:61]
	v_or_b32_e32 v56, v56, v148
	global_load_dwordx4 v[52:55], v[52:53], off
	s_nop 0
	global_load_dwordx2 v[84:85], v[62:63], off nt
	v_lshl_add_u64 v[62:63], s[14:15], 0, v[60:61]
	v_lshl_add_u64 v[72:73], s[12:13], 0, v[60:61]
	v_lshl_add_u64 v[60:61], s[26:27], 0, v[60:61]
	v_lshlrev_b64 v[56:57], 1, v[56:57]
	global_load_dwordx2 v[86:87], v[62:63], off nt
	global_load_dwordx2 v[82:83], v[72:73], off nt
	global_load_dwordx2 v[80:81], v[60:61], off nt
	v_lshl_add_u64 v[60:61], v[58:59], 0, v[158:159]
	v_lshl_add_u64 v[72:73], s[10:11], 0, v[56:57]
	global_load_dwordx4 v[60:63], v[60:61], off
	s_nop 0
	global_load_dwordx2 v[76:77], v[72:73], off nt
	v_lshl_add_u64 v[72:73], s[14:15], 0, v[56:57]
	v_lshl_add_u64 v[74:75], s[12:13], 0, v[56:57]
	v_lshl_add_u64 v[56:57], s[26:27], 0, v[56:57]
	global_load_dwordx2 v[78:79], v[72:73], off nt
	s_nop 0
	global_load_dwordx2 v[74:75], v[74:75], off nt
	s_nop 0
	global_load_dwordx2 v[72:73], v[56:57], off nt
	v_lshl_add_u64 v[56:57], v[58:59], 0, v[156:157]
	global_load_dwordx4 v[56:59], v[56:57], off
	s_waitcnt vmcnt(39)
	v_lshlrev_b32_e32 v166, 16, v100
	v_and_b32_e32 v167, 0xffff0000, v100
	s_waitcnt vmcnt(38)
	v_lshlrev_b32_e32 v168, 16, v102
	v_and_b32_e32 v169, 0xffff0000, v102
	v_lshlrev_b32_e32 v100, 16, v101
	v_and_b32_e32 v101, 0xffff0000, v101
	v_lshlrev_b32_e32 v102, 16, v103
	v_and_b32_e32 v103, 0xffff0000, v103
	v_pk_add_f32 v[166:167], v[166:167], v[168:169]
	s_waitcnt vmcnt(37)
	v_lshlrev_b32_e32 v168, 16, v104
	v_and_b32_e32 v169, 0xffff0000, v104
	s_waitcnt vmcnt(36)
	v_lshlrev_b32_e32 v170, 16, v106
	v_and_b32_e32 v171, 0xffff0000, v106
	v_pk_add_f32 v[100:101], v[100:101], v[102:103]
	v_lshlrev_b32_e32 v102, 16, v105
	v_and_b32_e32 v103, 0xffff0000, v105
	v_lshlrev_b32_e32 v104, 16, v107
	v_and_b32_e32 v105, 0xffff0000, v107
	v_pk_add_f32 v[168:169], v[168:169], v[170:171]
	v_pk_add_f32 v[102:103], v[102:103], v[104:105]
	v_pk_add_f32 v[166:167], v[166:167], v[168:169]
	v_pk_add_f32 v[168:169], v[100:101], v[102:103]
	s_waitcnt vmcnt(34)
	v_lshlrev_b32_e32 v100, 16, v108
	v_and_b32_e32 v101, 0xffff0000, v108
	s_waitcnt vmcnt(33)
	v_lshlrev_b32_e32 v102, 16, v110
	v_and_b32_e32 v103, 0xffff0000, v110
	v_pk_add_f32 v[100:101], v[100:101], v[102:103]
	s_waitcnt vmcnt(32)
	v_lshlrev_b32_e32 v102, 16, v112
	v_and_b32_e32 v103, 0xffff0000, v112
	s_waitcnt vmcnt(31)
	v_lshlrev_b32_e32 v104, 16, v114
	v_and_b32_e32 v105, 0xffff0000, v114
	v_pk_add_f32 v[102:103], v[102:103], v[104:105]
	v_lshlrev_b32_e32 v104, 16, v115
	v_pk_add_f32 v[170:171], v[100:101], v[102:103]
	v_lshlrev_b32_e32 v100, 16, v109
	v_and_b32_e32 v101, 0xffff0000, v109
	v_lshlrev_b32_e32 v102, 16, v111
	v_and_b32_e32 v103, 0xffff0000, v111
	v_pk_add_f32 v[100:101], v[100:101], v[102:103]
	v_lshlrev_b32_e32 v102, 16, v113
	v_and_b32_e32 v103, 0xffff0000, v113
	v_and_b32_e32 v105, 0xffff0000, v115
	v_pk_add_f32 v[102:103], v[102:103], v[104:105]
	s_waitcnt vmcnt(26)
	v_lshlrev_b32_e32 v104, 16, v122
	v_pk_add_f32 v[172:173], v[100:101], v[102:103]
	v_lshlrev_b32_e32 v100, 16, v116
	v_and_b32_e32 v101, 0xffff0000, v116
	v_lshlrev_b32_e32 v102, 16, v118
	v_and_b32_e32 v103, 0xffff0000, v118
	v_pk_add_f32 v[100:101], v[100:101], v[102:103]
	v_lshlrev_b32_e32 v102, 16, v120
	v_and_b32_e32 v103, 0xffff0000, v120
	v_and_b32_e32 v105, 0xffff0000, v122
	v_pk_add_f32 v[102:103], v[102:103], v[104:105]
	v_lshlrev_b32_e32 v104, 16, v123
	v_pk_add_f32 v[174:175], v[100:101], v[102:103]
	v_lshlrev_b32_e32 v100, 16, v117
	v_and_b32_e32 v101, 0xffff0000, v117
	v_lshlrev_b32_e32 v102, 16, v119
	v_and_b32_e32 v103, 0xffff0000, v119
	v_pk_add_f32 v[100:101], v[100:101], v[102:103]
	v_lshlrev_b32_e32 v102, 16, v121
	v_and_b32_e32 v103, 0xffff0000, v121
	v_and_b32_e32 v105, 0xffff0000, v123
	v_pk_add_f32 v[102:103], v[102:103], v[104:105]
	s_waitcnt vmcnt(21)
	v_lshlrev_b32_e32 v104, 16, v182
	v_pk_add_f32 v[176:177], v[100:101], v[102:103]
	v_mov_b32_e32 v102, v175
	v_mov_b32_e32 v103, v177
	v_mov_b32_e32 v100, v174
	v_mov_b32_e32 v101, v176
	v_pk_mul_f32 v[102:103], v[102:103], v[102:103]
	v_and_b32_e32 v105, 0xffff0000, v182
	v_pk_fma_f32 v[100:101], v[100:101], v[100:101], v[102:103]
	v_lshlrev_b32_e32 v102, 16, v126
	v_pk_add_f32 v[192:193], v[100:101], v[100:101] op_sel:[0,1] op_sel_hi:[1,0]
	v_lshlrev_b32_e32 v100, 16, v124
	v_and_b32_e32 v101, 0xffff0000, v124
	v_and_b32_e32 v103, 0xffff0000, v126
	v_pk_add_f32 v[100:101], v[100:101], v[102:103]
	v_lshlrev_b32_e32 v102, 16, v180
	v_and_b32_e32 v103, 0xffff0000, v180
	v_pk_add_f32 v[102:103], v[102:103], v[104:105]
	v_lshlrev_b32_e32 v104, 16, v183
	v_pk_add_f32 v[178:179], v[100:101], v[102:103]
	v_lshlrev_b32_e32 v100, 16, v125
	v_and_b32_e32 v101, 0xffff0000, v125
	v_lshlrev_b32_e32 v102, 16, v127
	v_and_b32_e32 v103, 0xffff0000, v127
	v_pk_add_f32 v[100:101], v[100:101], v[102:103]
	v_lshlrev_b32_e32 v102, 16, v181
	v_and_b32_e32 v103, 0xffff0000, v181
	v_and_b32_e32 v105, 0xffff0000, v183
	v_pk_add_f32 v[102:103], v[102:103], v[104:105]
	s_waitcnt vmcnt(16)
	v_lshlrev_b32_e32 v104, 16, v96
	v_pk_add_f32 v[180:181], v[100:101], v[102:103]
	v_mul_f32_e32 v100, v179, v179
	v_pk_fma_f32 v[198:199], v[178:179], v[178:179], v[100:101] op_sel_hi:[1,1,0]
	v_mul_f32_e32 v100, v181, v181
	v_pk_fma_f32 v[200:201], v[180:181], v[180:181], v[100:101] op_sel_hi:[1,1,0]
	v_lshlrev_b32_e32 v100, 16, v184
	v_and_b32_e32 v101, 0xffff0000, v184
	v_lshlrev_b32_e32 v102, 16, v186
	v_and_b32_e32 v103, 0xffff0000, v186
	v_pk_add_f32 v[100:101], v[100:101], v[102:103]
	v_lshlrev_b32_e32 v102, 16, v98
	v_and_b32_e32 v103, 0xffff0000, v98
	v_and_b32_e32 v105, 0xffff0000, v96
	v_pk_add_f32 v[102:103], v[102:103], v[104:105]
	v_lshlrev_b32_e32 v98, 16, v99
	v_pk_add_f32 v[182:183], v[100:101], v[102:103]
	v_lshlrev_b32_e32 v100, 16, v185
	v_and_b32_e32 v101, 0xffff0000, v185
	v_lshlrev_b32_e32 v102, 16, v187
	v_and_b32_e32 v103, 0xffff0000, v187
	v_and_b32_e32 v99, 0xffff0000, v99
	v_lshlrev_b32_e32 v96, 16, v97
	v_and_b32_e32 v97, 0xffff0000, v97
	v_pk_add_f32 v[100:101], v[100:101], v[102:103]
	v_pk_add_f32 v[96:97], v[98:99], v[96:97]
	s_waitcnt vmcnt(13)
	v_lshlrev_b32_e32 v98, 16, v94
	v_pk_add_f32 v[184:185], v[100:101], v[96:97]
	v_lshlrev_b32_e32 v96, 16, v92
	v_and_b32_e32 v97, 0xffff0000, v92
	v_and_b32_e32 v99, 0xffff0000, v94
	v_pk_add_f32 v[96:97], v[96:97], v[98:99]
	s_waitcnt vmcnt(12)
	v_lshlrev_b32_e32 v98, 16, v90
	v_and_b32_e32 v99, 0xffff0000, v90
	s_waitcnt vmcnt(11)
	v_lshlrev_b32_e32 v100, 16, v88
	v_and_b32_e32 v101, 0xffff0000, v88
	v_lshlrev_b32_e32 v92, 16, v93
	v_and_b32_e32 v93, 0xffff0000, v93
	v_lshlrev_b32_e32 v94, 16, v95
	v_and_b32_e32 v95, 0xffff0000, v95
	v_lshlrev_b32_e32 v90, 16, v91
	v_and_b32_e32 v91, 0xffff0000, v91
	v_lshlrev_b32_e32 v88, 16, v89
	v_and_b32_e32 v89, 0xffff0000, v89
	v_pk_add_f32 v[98:99], v[98:99], v[100:101]
	v_pk_add_f32 v[92:93], v[92:93], v[94:95]
	v_pk_add_f32 v[88:89], v[90:91], v[88:89]
	v_pk_add_f32 v[186:187], v[96:97], v[98:99]
	v_pk_add_f32 v[188:189], v[92:93], v[88:89]
	v_mov_b32_e32 v90, v187
	v_mov_b32_e32 v91, v189
	v_mov_b32_e32 v88, v186
	v_mov_b32_e32 v89, v188
	v_pk_mul_f32 v[90:91], v[90:91], v[90:91]
	s_waitcnt vmcnt(6)
	v_lshlrev_b32_e32 v92, 16, v80
	v_pk_fma_f32 v[88:89], v[88:89], v[88:89], v[90:91]
	v_lshlrev_b32_e32 v90, 16, v86
	v_pk_add_f32 v[206:207], v[88:89], v[88:89] op_sel:[0,1] op_sel_hi:[1,0]
	v_lshlrev_b32_e32 v88, 16, v84
	v_and_b32_e32 v89, 0xffff0000, v84
	v_and_b32_e32 v91, 0xffff0000, v86
	v_pk_add_f32 v[88:89], v[88:89], v[90:91]
	v_lshlrev_b32_e32 v90, 16, v82
	v_and_b32_e32 v91, 0xffff0000, v82
	v_and_b32_e32 v93, 0xffff0000, v80
	v_pk_add_f32 v[90:91], v[90:91], v[92:93]
	v_lshlrev_b32_e32 v84, 16, v85
	v_and_b32_e32 v85, 0xffff0000, v85
	v_lshlrev_b32_e32 v86, 16, v87
	v_and_b32_e32 v87, 0xffff0000, v87
	v_lshlrev_b32_e32 v82, 16, v83
	v_and_b32_e32 v83, 0xffff0000, v83
	v_lshlrev_b32_e32 v80, 16, v81
	v_and_b32_e32 v81, 0xffff0000, v81
	v_pk_add_f32 v[190:191], v[88:89], v[90:91]
	v_pk_add_f32 v[84:85], v[84:85], v[86:87]
	v_pk_add_f32 v[80:81], v[82:83], v[80:81]
	s_waitcnt vmcnt(3)
	v_lshlrev_b32_e32 v82, 16, v78
	v_pk_add_f32 v[194:195], v[84:85], v[80:81]
	v_mul_f32_e32 v80, v191, v191
	v_pk_fma_f32 v[208:209], v[190:191], v[190:191], v[80:81] op_sel_hi:[1,1,0]
	v_mul_f32_e32 v80, v195, v195
	v_pk_fma_f32 v[210:211], v[194:195], v[194:195], v[80:81] op_sel_hi:[1,1,0]
	v_lshlrev_b32_e32 v80, 16, v76
	v_and_b32_e32 v81, 0xffff0000, v76
	v_and_b32_e32 v83, 0xffff0000, v78
	v_pk_add_f32 v[80:81], v[80:81], v[82:83]
	s_waitcnt vmcnt(2)
	v_lshlrev_b32_e32 v82, 16, v74
	v_and_b32_e32 v83, 0xffff0000, v74
	s_waitcnt vmcnt(1)
	v_lshlrev_b32_e32 v84, 16, v72
	v_and_b32_e32 v85, 0xffff0000, v72
	v_lshlrev_b32_e32 v76, 16, v77
	v_and_b32_e32 v77, 0xffff0000, v77
	v_lshlrev_b32_e32 v78, 16, v79
	v_and_b32_e32 v79, 0xffff0000, v79
	v_lshlrev_b32_e32 v74, 16, v75
	v_and_b32_e32 v75, 0xffff0000, v75
	v_lshlrev_b32_e32 v72, 16, v73
	v_and_b32_e32 v73, 0xffff0000, v73
	v_pk_add_f32 v[82:83], v[82:83], v[84:85]
	v_pk_add_f32 v[76:77], v[76:77], v[78:79]
	v_pk_add_f32 v[72:73], v[74:75], v[72:73]
	v_pk_add_f32 v[196:197], v[80:81], v[82:83]
	v_pk_add_f32 v[212:213], v[76:77], v[72:73]
	v_pk_mul_f32 v[202:203], v[182:183], v[182:183]
	v_pk_mul_f32 v[204:205], v[184:185], v[184:185]
	v_pk_mul_f32 v[214:215], v[196:197], v[196:197]
	v_pk_mul_f32 v[216:217], v[212:213], v[212:213]
	v_lshl_add_u64 v[218:219], v[64:65], 0, s[54:55]
	v_lshl_add_u64 v[64:65], v[64:65], 0, s[56:57]
	v_lshl_add_u64 v[72:73], v[218:219], 0, v[134:135]
	v_lshl_add_u64 v[74:75], v[64:65], 0, v[134:135]
	global_load_dwordx4 v[120:123], v[72:73], off
	global_load_dwordx4 v[124:127], v[74:75], off
	v_lshl_add_u64 v[72:73], v[218:219], 0, v[66:67]
	v_lshl_add_u64 v[66:67], v[64:65], 0, v[66:67]
	global_load_dwordx4 v[112:115], v[72:73], off
	global_load_dwordx4 v[116:119], v[66:67], off
	v_lshl_add_u64 v[66:67], v[218:219], 0, v[68:69]
	v_lshl_add_u64 v[68:69], v[64:65], 0, v[68:69]
	global_load_dwordx4 v[104:107], v[66:67], off
	global_load_dwordx4 v[108:111], v[68:69], off
	v_lshl_add_u64 v[66:67], v[218:219], 0, v[70:71]
	v_lshl_add_u64 v[68:69], v[64:65], 0, v[70:71]
	global_load_dwordx4 v[96:99], v[66:67], off
	global_load_dwordx4 v[100:103], v[68:69], off
	v_lshl_add_u64 v[66:67], v[218:219], 0, v[162:163]
	v_lshl_add_u64 v[68:69], v[64:65], 0, v[162:163]
	global_load_dwordx4 v[88:91], v[66:67], off
	global_load_dwordx4 v[92:95], v[68:69], off
	v_lshl_add_u64 v[66:67], v[218:219], 0, v[160:161]
	v_lshl_add_u64 v[68:69], v[64:65], 0, v[160:161]
	global_load_dwordx4 v[80:83], v[66:67], off
	global_load_dwordx4 v[84:87], v[68:69], off
	v_lshl_add_u64 v[66:67], v[218:219], 0, v[158:159]
	v_lshl_add_u64 v[68:69], v[64:65], 0, v[158:159]
	global_load_dwordx4 v[72:75], v[66:67], off
	global_load_dwordx4 v[76:79], v[68:69], off
	v_lshl_add_u64 v[66:67], v[218:219], 0, v[156:157]
	v_lshl_add_u64 v[68:69], v[64:65], 0, v[156:157]
	global_load_dwordx4 v[64:67], v[66:67], off
	s_nop 0
	global_load_dwordx4 v[68:71], v[68:69], off
	v_mov_b32_e32 v222, v169
	v_mov_b32_e32 v223, v173
	v_mov_b32_e32 v218, v167
	v_mov_b32_e32 v219, v171
	v_mov_b32_e32 v220, v168
	v_mov_b32_e32 v221, v172
	v_pk_mul_f32 v[222:223], v[222:223], v[222:223]
	v_pk_mul_f32 v[218:219], v[218:219], v[218:219]
	v_pk_fma_f32 v[220:221], v[220:221], v[220:221], v[222:223]
	v_mov_b32_e32 v222, v166
	v_mov_b32_e32 v223, v170
	v_pk_fma_f32 v[218:219], v[222:223], v[222:223], v[218:219]
	v_mov_b32_e32 v199, v204
	v_pk_add_f32 v[218:219], v[218:219], v[220:221]
	v_mov_b32_e32 v201, v205
	v_pk_add_f32 v[218:219], v[218:219], v[218:219] op_sel:[0,1] op_sel_hi:[1,0]
	v_mov_b32_e32 v193, v203
	v_mov_b32_e32 v219, v202
	v_pk_add_f32 v[198:199], v[198:199], v[200:201]
	v_pk_add_f32 v[192:193], v[218:219], v[192:193]
	v_mov_b32_e32 v209, v216
	v_pk_add_f32 v[192:193], v[192:193], v[198:199]
	v_mov_b32_e32 v211, v217
	v_pk_add_f32 v[192:193], v[192:193], v[192:193] op_sel:[0,1] op_sel_hi:[1,0]
	v_mov_b32_e32 v207, v215
	v_mov_b32_e32 v193, v214
	v_pk_add_f32 v[198:199], v[208:209], v[210:211]
	v_pk_add_f32 v[192:193], v[192:193], v[206:207]
	s_nop 0
	v_pk_add_f32 v[192:193], v[192:193], v[198:199]
	s_nop 0
	v_add_f32_e32 v147, v192, v193
	ds_bpermute_b32 v149, v129, v147
	v_lshl_add_u64 v[164:165], s[48:49], 0, v[164:165]
	v_lshl_add_u64 v[192:193], v[164:165], 0, v[134:135]
	v_lshl_add_u64 v[162:163], v[164:165], 0, v[162:163]
	s_waitcnt lgkmcnt(0)
	v_add_f32_e32 v147, v147, v149
	ds_bpermute_b32 v149, v133, v147
	s_waitcnt lgkmcnt(0)
	v_add_f32_e32 v147, v147, v149
	ds_bpermute_b32 v149, v137, v147
	s_waitcnt lgkmcnt(0)
	v_add_f32_e32 v147, v147, v149
	ds_bpermute_b32 v149, v139, v147
	s_waitcnt lgkmcnt(0)
	v_add_f32_e32 v147, v147, v149
	ds_bpermute_b32 v149, v141, v147
	s_waitcnt lgkmcnt(0)
	v_add_f32_e32 v147, v147, v149
	ds_bpermute_b32 v149, v143, v147
	s_waitcnt lgkmcnt(0)
	v_add_f32_e32 v147, v147, v149
	v_fmamk_f32 v147, v147, 0x3a000000, v145
	v_mul_f32_e32 v149, 0x4b800000, v147
	v_cmp_gt_f32_e32 vcc, s59, v147
	s_nop 1
	v_cndmask_b32_e32 v147, v147, v149, vcc
	v_rsq_f32_e32 v147, v147
	s_nop 0
	v_mul_f32_e32 v134, 0x45800000, v147
	v_cndmask_b32_e32 v134, v147, v134, vcc
	v_pk_mul_f32 v[166:167], v[166:167], v[134:135] op_sel_hi:[1,0]
	v_pk_mul_f32 v[168:169], v[168:169], v[134:135] op_sel_hi:[1,0]
	v_pk_mul_f32 v[186:187], v[186:187], v[134:135] op_sel_hi:[1,0]
	v_pk_fma_f32 v[24:25], v[32:33], v[166:167], v[24:25]
	v_pk_mul_f32 v[32:33], v[188:189], v[134:135] op_sel_hi:[1,0]
	v_pk_mul_f32 v[170:171], v[170:171], v[134:135] op_sel_hi:[1,0]
	v_pk_mul_f32 v[172:173], v[172:173], v[134:135] op_sel_hi:[1,0]
	v_pk_mul_f32 v[174:175], v[174:175], v[134:135] op_sel_hi:[1,0]
	v_pk_mul_f32 v[176:177], v[176:177], v[134:135] op_sel_hi:[1,0]
	v_pk_mul_f32 v[178:179], v[178:179], v[134:135] op_sel_hi:[1,0]
	v_pk_mul_f32 v[180:181], v[180:181], v[134:135] op_sel_hi:[1,0]
	v_pk_mul_f32 v[182:183], v[182:183], v[134:135] op_sel_hi:[1,0]
	v_pk_mul_f32 v[184:185], v[184:185], v[134:135] op_sel_hi:[1,0]
	v_pk_fma_f32 v[26:27], v[34:35], v[168:169], v[26:27]
	v_pk_fma_f32 v[10:11], v[54:55], v[32:33], v[10:11]
	v_pk_fma_f32 v[8:9], v[52:53], v[186:187], v[8:9]
	v_lshl_add_u64 v[32:33], v[164:165], 0, v[160:161]
	v_pk_fma_f32 v[22:23], v[38:39], v[172:173], v[22:23]
	v_pk_fma_f32 v[20:21], v[36:37], v[170:171], v[20:21]
	v_pk_fma_f32 v[18:19], v[42:43], v[176:177], v[18:19]
	v_pk_fma_f32 v[16:17], v[40:41], v[174:175], v[16:17]
	v_pk_fma_f32 v[14:15], v[46:47], v[180:181], v[14:15]
	v_pk_fma_f32 v[12:13], v[44:45], v[178:179], v[12:13]
	v_pk_fma_f32 v[30:31], v[50:51], v[184:185], v[30:31]
	v_pk_fma_f32 v[28:29], v[48:49], v[182:183], v[28:29]
	global_store_dwordx4 v[192:193], v[24:27], off
	global_store_dwordx4 v[192:193], v[20:23], off offset:1024
	global_store_dwordx4 v[192:193], v[16:19], off offset:2048
	global_store_dwordx4 v[192:193], v[12:15], off offset:3072
	global_store_dwordx4 v[162:163], v[28:31], off
	global_store_dwordx4 v[32:33], v[8:11], off
	v_pk_mul_f32 v[32:33], v[190:191], v[134:135] op_sel_hi:[1,0]
	v_pk_mul_f32 v[34:35], v[194:195], v[134:135] op_sel_hi:[1,0]
	v_pk_fma_f32 v[4:5], v[60:61], v[32:33], v[4:5]
	v_pk_fma_f32 v[6:7], v[62:63], v[34:35], v[6:7]
	v_lshl_add_u64 v[32:33], v[164:165], 0, v[158:159]
	global_store_dwordx4 v[32:33], v[4:7], off
	v_pk_mul_f32 v[32:33], v[196:197], v[134:135] op_sel_hi:[1,0]
	v_pk_mul_f32 v[34:35], v[212:213], v[134:135] op_sel_hi:[1,0]
	s_waitcnt vmcnt(23)
	v_pk_fma_f32 v[0:1], v[56:57], v[32:33], v[0:1]
	v_pk_fma_f32 v[2:3], v[58:59], v[34:35], v[2:3]
	v_lshl_add_u64 v[32:33], v[164:165], 0, v[156:157]
	global_store_dwordx4 v[32:33], v[0:3], off
	v_mov_b32_e32 v34, v25
	v_mov_b32_e32 v35, v21
	v_mov_b32_e32 v32, v24
	v_mov_b32_e32 v33, v20
	v_pk_mul_f32 v[34:35], v[34:35], v[34:35]
	v_mov_b32_e32 v36, v27
	v_mov_b32_e32 v37, v23
	v_pk_fma_f32 v[32:33], v[32:33], v[32:33], v[34:35]
	v_mov_b32_e32 v34, v26
	v_mov_b32_e32 v35, v22
	v_pk_mul_f32 v[36:37], v[36:37], v[36:37]
	v_readfirstlane_b32 s83, v237
	s_lshl_b32 s83, s83, 1
	s_add_u32 s83, s83, s86
	s_add_u32 s83, s83, s94
	s_lshl_b32 s83, s83, 3
	s_sub_u32 s84, s83, s82
	s_mov_b32 s82, s83
	s_mov_b32 s85, 0
	s_mov_b64 s[6:7], s[84:85]
	s_lshl_b64 s[28:29], s[84:85], 13
	v_lshl_add_u64 v[130:131], v[130:131], 0, s[6:7]
	v_pk_fma_f32 v[34:35], v[34:35], v[34:35], v[36:37]
	v_pk_mul_f32 v[36:37], v[16:17], v[16:17]
	v_pk_add_f32 v[32:33], v[32:33], v[34:35]
	v_pk_mul_f32 v[34:35], v[18:19], v[18:19]
	v_pk_add_f32 v[32:33], v[32:33], v[32:33] op_sel_hi:[0,1]
	v_pk_mov_b32 v[38:39], v[36:37], v[34:35] op_sel:[1,0]
	v_mov_b32_e32 v37, v35
	v_mul_f32_e32 v32, v12, v12
	v_pk_add_f32 v[34:35], v[38:39], v[36:37]
	v_pk_fma_f32 v[36:37], v[12:13], v[12:13], v[32:33] op_sel_hi:[1,1,0]
	v_mul_f32_e32 v32, v14, v14
	v_pk_add_f32 v[34:35], v[34:35], v[34:35] op_sel_hi:[0,1]
	v_pk_fma_f32 v[38:39], v[14:15], v[14:15], v[32:33] op_sel_hi:[1,1,0]
	v_mul_f32_e32 v36, v28, v28
	v_mul_f32_e32 v38, v29, v29
	v_mul_f32_e32 v34, v30, v30
	v_mul_f32_e32 v32, v31, v31
	v_pk_add_f32 v[36:37], v[36:37], v[38:39]
	v_pk_add_f32 v[32:33], v[34:35], v[32:33]
	v_pk_mul_f32 v[34:35], v[10:11], v[10:11]
	v_pk_add_f32 v[32:33], v[36:37], v[32:33]
	v_pk_mul_f32 v[36:37], v[8:9], v[8:9]
	v_pk_add_f32 v[32:33], v[32:33], v[32:33] op_sel_hi:[0,1]
	v_pk_mov_b32 v[38:39], v[36:37], v[34:35] op_sel:[1,0]
	v_mov_b32_e32 v37, v35
	v_mul_f32_e32 v32, v4, v4
	v_pk_add_f32 v[34:35], v[38:39], v[36:37]
	v_pk_fma_f32 v[36:37], v[4:5], v[4:5], v[32:33] op_sel_hi:[1,1,0]
	v_mul_f32_e32 v32, v6, v6
	v_pk_add_f32 v[34:35], v[34:35], v[34:35] op_sel_hi:[0,1]
	v_pk_fma_f32 v[38:39], v[6:7], v[6:7], v[32:33] op_sel_hi:[1,1,0]
	v_mul_f32_e32 v36, v0, v0
	v_mul_f32_e32 v38, v1, v1
	v_mul_f32_e32 v34, v2, v2
	v_mul_f32_e32 v32, v3, v3
	v_pk_add_f32 v[36:37], v[36:37], v[38:39]
	v_pk_add_f32 v[32:33], v[34:35], v[32:33]
	v_lshlrev_b64 v[34:35], 12, v[154:155]
	v_pk_add_f32 v[32:33], v[36:37], v[32:33]
	v_lshl_add_u64 v[152:153], v[152:153], 0, s[28:29]
	v_add_f32_e32 v32, v32, v33
	ds_bpermute_b32 v33, v129, v32
	s_waitcnt lgkmcnt(0)
	v_add_f32_e32 v32, v32, v33
	ds_bpermute_b32 v33, v133, v32
	s_waitcnt lgkmcnt(0)
	v_add_f32_e32 v32, v32, v33
	ds_bpermute_b32 v33, v137, v32
	s_waitcnt lgkmcnt(0)
	v_add_f32_e32 v32, v32, v33
	ds_bpermute_b32 v33, v139, v32
	s_waitcnt lgkmcnt(0)
	v_add_f32_e32 v32, v32, v33
	ds_bpermute_b32 v33, v141, v32
	s_waitcnt lgkmcnt(0)
	v_add_f32_e32 v32, v32, v33
	ds_bpermute_b32 v33, v143, v32
	s_waitcnt lgkmcnt(0)
	v_add_f32_e32 v32, v32, v33
	v_fmamk_f32 v32, v32, 0x3a000000, v145
	v_mul_f32_e32 v33, 0x4b800000, v32
	v_cmp_gt_f32_e32 vcc, s59, v32
	s_nop 1
	v_cndmask_b32_e32 v32, v32, v33, vcc
	v_rsq_f32_e32 v32, v32
	s_nop 0
	v_mul_f32_e32 v33, 0x45800000, v32
	v_cndmask_b32_e32 v32, v32, v33, vcc
	v_pk_mul_f32 v[24:25], v[24:25], v[32:33] op_sel_hi:[1,0]
	v_pk_mul_f32 v[26:27], v[26:27], v[32:33] op_sel_hi:[1,0]
	v_pk_mul_f32 v[12:13], v[12:13], v[32:33] op_sel_hi:[1,0]
	v_pk_mul_f32 v[14:15], v[14:15], v[32:33] op_sel_hi:[1,0]
	s_waitcnt vmcnt(22)
	v_pk_fma_f32 v[26:27], v[122:123], v[26:27], v[126:127]
	v_pk_fma_f32 v[24:25], v[120:121], v[24:25], v[124:125]
	s_waitcnt vmcnt(16)
	v_pk_fma_f32 v[14:15], v[98:99], v[14:15], v[102:103]
	v_pk_fma_f32 v[12:13], v[96:97], v[12:13], v[100:101]
	v_cvt_pk_bf16_f32 v24, v24, v25
	v_cvt_pk_bf16_f32 v25, v26, v27
	v_lshl_add_u64 v[26:27], v[150:151], 0, v[34:35]
	v_cvt_pk_bf16_f32 v12, v12, v13
	v_cvt_pk_bf16_f32 v13, v14, v15
	v_pk_mul_f32 v[20:21], v[20:21], v[32:33] op_sel_hi:[1,0]
	v_pk_mul_f32 v[22:23], v[22:23], v[32:33] op_sel_hi:[1,0]
	v_pk_mul_f32 v[16:17], v[16:17], v[32:33] op_sel_hi:[1,0]
	v_pk_mul_f32 v[18:19], v[18:19], v[32:33] op_sel_hi:[1,0]
	global_store_dwordx2 v[26:27], v[12:13], off offset:1536
	v_pk_mul_f32 v[12:13], v[28:29], v[32:33] op_sel_hi:[1,0]
	v_pk_mul_f32 v[14:15], v[30:31], v[32:33] op_sel_hi:[1,0]
	v_pk_mul_f32 v[8:9], v[8:9], v[32:33] op_sel_hi:[1,0]
	v_pk_mul_f32 v[10:11], v[10:11], v[32:33] op_sel_hi:[1,0]
	v_pk_mul_f32 v[4:5], v[4:5], v[32:33] op_sel_hi:[1,0]
	v_pk_mul_f32 v[6:7], v[6:7], v[32:33] op_sel_hi:[1,0]
	v_pk_mul_f32 v[0:1], v[0:1], v[32:33] op_sel_hi:[1,0]
	v_pk_mul_f32 v[2:3], v[2:3], v[32:33] op_sel_hi:[1,0]
	v_pk_fma_f32 v[22:23], v[114:115], v[22:23], v[118:119]
	v_pk_fma_f32 v[20:21], v[112:113], v[20:21], v[116:117]
	v_pk_fma_f32 v[18:19], v[106:107], v[18:19], v[110:111]
	v_pk_fma_f32 v[16:17], v[104:105], v[16:17], v[108:109]
	s_waitcnt vmcnt(15)
	v_pk_fma_f32 v[14:15], v[90:91], v[14:15], v[94:95]
	v_pk_fma_f32 v[12:13], v[88:89], v[12:13], v[92:93]
	s_waitcnt vmcnt(13)
	v_pk_fma_f32 v[10:11], v[82:83], v[10:11], v[86:87]
	v_pk_fma_f32 v[8:9], v[80:81], v[8:9], v[84:85]
	s_waitcnt vmcnt(11)
	v_pk_fma_f32 v[6:7], v[74:75], v[6:7], v[78:79]
	v_pk_fma_f32 v[4:5], v[72:73], v[4:5], v[76:77]
	s_waitcnt vmcnt(9)
	v_pk_fma_f32 v[2:3], v[66:67], v[2:3], v[70:71]
	v_pk_fma_f32 v[0:1], v[64:65], v[0:1], v[68:69]
	v_cmp_lt_i32_e32 vcc, s60, v130
	v_cvt_pk_bf16_f32 v20, v20, v21
	v_cvt_pk_bf16_f32 v21, v22, v23
	v_cvt_pk_bf16_f32 v16, v16, v17
	v_cvt_pk_bf16_f32 v17, v18, v19
	v_cvt_pk_bf16_f32 v12, v12, v13
	v_cvt_pk_bf16_f32 v13, v14, v15
	v_cvt_pk_bf16_f32 v8, v8, v9
	v_cvt_pk_bf16_f32 v9, v10, v11
	v_cvt_pk_bf16_f32 v4, v4, v5
	v_cvt_pk_bf16_f32 v5, v6, v7
	v_cvt_pk_bf16_f32 v0, v0, v1
	v_cvt_pk_bf16_f32 v1, v2, v3
	s_or_b64 s[30:31], vcc, s[30:31]
	global_store_dwordx2 v[26:27], v[24:25], off
	global_store_dwordx2 v[26:27], v[20:21], off offset:512
	global_store_dwordx2 v[26:27], v[16:17], off offset:1024
	global_store_dwordx2 v[26:27], v[12:13], off offset:2048
	global_store_dwordx2 v[26:27], v[8:9], off offset:2560
	global_store_dwordx2 v[26:27], v[4:5], off offset:3072
	global_store_dwordx2 v[26:27], v[0:1], off offset:3584
	s_andn2_b64 exec, exec, s[30:31]
	s_cbranch_execz .LBB0_742
